# v020 with the 8 K-read address adds moved from the exp-bound softmax segment into the previous tile's load segment (segment rebalancing)
# baseline (speedup 1.0000x reference)
; #define SBAR() __builtin_amdgcn_sched_barrier(0)
; #define NAM(P0, P1, t) do { if constexpr (NA) na_mask(P0, P1, kr_lo + (t), r0, qrow, qc, c0, hi, bl); } while (0)
; #define PSM(P0, P1, MN, AL) do { if constexpr (NA) partialSM(P0, P1, m_reg, MN, AL); else { AL = 1.f; _Pragma("unroll") for (int r = 0; r < 16; ++r) P0[r] = __builtin_amdgcn_exp2f(P0[r]); } } while (0)
; #define RESCN(a) do { if constexpr (NA) RESC(a); } while (0)
; #define VM0() asm volatile("s_waitcnt vmcnt(0)" ::: "memory")
; #define NAM(P0, P1, t) do { if constexpr (NA) na_mask(P0, P1, kr_lo + (t), r0, qrow, qc, c0, hi, bl); } while (0)
; #define PSM(P0, P1, MN, AL) do { if constexpr (NA) partialSM(P0, P1, m_reg, MN, AL); else { AL = 1.f; _Pragma("unroll") for (int r = 0; r < 16; ++r) P0[r] = __builtin_amdgcn_exp2f(P0[r]); } } while (0)
; #define RESCN(a) do { if constexpr (NA) RESC(a); } while (0)
; template <bool NA, int ROWB>
; __device__ __forceinline__ void attn_dma(const bf16* __restrict__ Qb, const bf16* __restrict__ Kh, const bf16* __restrict__ Vh, bf16* __restrict__ Ob, int NT, char* lds, const int tid, float* __restrict__ ssb, int qrow0, int kr_lo, const float* bl) {
;     ...
;   DMA_TILE(0, 0); DMA_TILE(1, 1); VM0(); __syncthreads();
;   qkt<false>(pA0, pA1, (const bf16*)K_lds, qr, nullptr, r32, hi); NAM(pA0, pA1, 0); PSM(pA0, pA1, mnA, alA);
;   int bp = 0, bc = 1, bn = 2;
;   for (int t = 1; t + 1 < NT; t += 2) {
;     DMA_TILE(t + 1, bn);
;     SBAR(); qkt<false>(pB0, pB1, (const bf16*)(K_lds + bc * SHM_K), qr, nullptr, r32, hi); NAM(pB0, pB1, t);
;     finishSM(pA0, pA1, alA, l_reg, pa0, pa1, pa2, pa3); SBAR();
;     pv_d0(o, vb0 + bp * (int)SHM_V, pa0, pa1, pa2, pa3); PSM(pB0, pB1, mnB, alB); RESCN(alB);
;     VM0(); __syncthreads();
;     bp = bc; bc = bn; bn = NEXTB(bn);
;     if (t + 2 < NT) DMA_TILE(t + 2, bn);
;     SBAR(); qkt<false>(pA0, pA1, (const bf16*)(K_lds + bc * SHM_K), qr, nullptr, r32, hi); NAM(pA0, pA1, t + 1);
;     finishSM(pB0, pB1, alB, l_reg, pa0, pa1, pa2, pa3); SBAR();
;     pv_d0(o, vb0 + bp * (int)SHM_V, pa0, pa1, pa2, pa3); PSM(pA0, pA1, mnA, alA); RESCN(alA);
.Lgqa_lead:
	v_mov_b32_e32 v80, v212
	v_mov_b32_e32 v81, v214
	v_mov_b32_e32 v82, v210
	v_mov_b32_e32 v83, v213
	v_mov_b32_e32 v84, v208
	v_mov_b32_e32 v85, v211
	v_mov_b32_e32 v86, v207
	v_mov_b32_e32 v87, v209
	v_mov_b32_e32 v88, v203
	v_mov_b32_e32 v89, v206
	v_mov_b32_e32 v90, v198
	v_mov_b32_e32 v91, v205
	v_mov_b32_e32 v92, v196
	v_mov_b32_e32 v93, v199
	v_mov_b32_e32 v94, v175
	v_mov_b32_e32 v95, v197
	v_add_u32_e32 v215, s24, v195
	ds_read_b64_tr_b16 v[146:147], v215 offset:0
	ds_read_b64_tr_b16 v[148:149], v215 offset:2048
	ds_read_b64_tr_b16 v[150:151], v215 offset:4096
	ds_read_b64_tr_b16 v[152:153], v215 offset:6144
	ds_read_b64_tr_b16 v[154:155], v215 offset:8192
	ds_read_b64_tr_b16 v[156:157], v215 offset:10240
	ds_read_b64_tr_b16 v[158:159], v215 offset:12288
	ds_read_b64_tr_b16 v[160:161], v215 offset:14336
	ds_read_b64_tr_b16 v[176:177], v215 offset:512
	ds_read_b64_tr_b16 v[178:179], v215 offset:2560
	ds_read_b64_tr_b16 v[180:181], v215 offset:4608
	ds_read_b64_tr_b16 v[182:183], v215 offset:6656
	ds_read_b64_tr_b16 v[216:217], v215 offset:8704
	ds_read_b64_tr_b16 v[218:219], v215 offset:10752
	ds_read_b64_tr_b16 v[220:221], v215 offset:12800
	ds_read_b64_tr_b16 v[222:223], v215 offset:14848
	ds_read_b64_tr_b16 v[224:225], v215 offset:1024
	ds_read_b64_tr_b16 v[226:227], v215 offset:3072
	ds_read_b64_tr_b16 v[234:235], v215 offset:5120
	ds_read_b64_tr_b16 v[236:237], v215 offset:7168
	ds_read_b64_tr_b16 v[240:241], v215 offset:9216
	ds_read_b64_tr_b16 v[242:243], v215 offset:11264
	ds_read_b64_tr_b16 v[244:245], v215 offset:13312
	ds_read_b64_tr_b16 v[246:247], v215 offset:15360
	ds_read_b64_tr_b16 v[248:249], v215 offset:1536
	ds_read_b64_tr_b16 v[250:251], v215 offset:3584
	ds_read_b64_tr_b16 v[196:197], v215 offset:5632
	ds_read_b64_tr_b16 v[198:199], v215 offset:7680
	ds_read_b64_tr_b16 v[206:207], v215 offset:9728
	ds_read_b64_tr_b16 v[208:209], v215 offset:11776
	ds_read_b64_tr_b16 v[210:211], v215 offset:13824
	ds_read_b64_tr_b16 v[212:213], v215 offset:15872
	v_add_u32_e32 v229, s0, v187
	v_add_u32_e32 v230, s0, v188
	v_add_u32_e32 v232, s0, v189
	v_add_u32_e32 v238, s0, v190
	v_add_u32_e32 v203, s0, v191
	v_add_u32_e32 v205, s0, v192
	v_add_u32_e32 v214, s0, v193
	v_add_u32_e32 v175, s0, v194
	v_exp_f32_e32 v64, v64
	v_exp_f32_e32 v65, v65
	v_exp_f32_e32 v66, v66
	v_exp_f32_e32 v67, v67
	v_exp_f32_e32 v68, v68
	v_exp_f32_e32 v69, v69
	v_exp_f32_e32 v70, v70
	v_exp_f32_e32 v71, v71
	v_exp_f32_e32 v72, v72
	v_exp_f32_e32 v73, v73
	v_exp_f32_e32 v74, v74
	v_exp_f32_e32 v75, v75
	v_exp_f32_e32 v76, v76
	v_exp_f32_e32 v77, v77
	v_exp_f32_e32 v78, v78
	v_exp_f32_e32 v79, v79
	v_cvt_pk_bf16_f32 v96, v80, v81
	v_cvt_pk_bf16_f32 v97, v82, v83
	v_cvt_pk_bf16_f32 v98, v84, v85
	v_cvt_pk_bf16_f32 v99, v86, v87
	v_cvt_pk_bf16_f32 v100, v88, v89
	v_cvt_pk_bf16_f32 v101, v90, v91
	v_cvt_pk_bf16_f32 v102, v92, v93
	v_cvt_pk_bf16_f32 v103, v94, v95
	v_cvt_pk_bf16_f32 v104, v64, v65
	v_cvt_pk_bf16_f32 v105, v66, v67
	v_cvt_pk_bf16_f32 v106, v68, v69
	v_cvt_pk_bf16_f32 v107, v70, v71
	v_cvt_pk_bf16_f32 v108, v72, v73
	v_cvt_pk_bf16_f32 v109, v74, v75
	v_cvt_pk_bf16_f32 v110, v76, v77
	v_cvt_pk_bf16_f32 v111, v78, v79
	s_add_u32 s98, s40, s18
	s_addc_u32 s99, s41, 0
	s_add_i32 s25, s17, s4
	s_add_i32 m0, s25, 0xc000
	s_nop 0
	global_load_lds_dwordx4 v164, s[98:99]
	s_add_i32 m0, s25, 0xc400
	s_nop 0
	global_load_lds_dwordx4 v168, s[98:99]
	s_waitcnt lgkmcnt(0)
	s_barrier
	s_setprio 1
	v_mfma_f32_32x32x16_bf16 v[0:15], v[96:99], v[146:149], v[0:15]
	ds_read_b128 v[146:149], v229 offset:49152
	v_mfma_f32_32x32x16_bf16 v[0:15], v[100:103], v[150:153], v[0:15]
	ds_read_b128 v[150:153], v229 offset:57344
	v_mfma_f32_32x32x16_bf16 v[0:15], v[104:107], v[154:157], v[0:15]
	ds_read_b128 v[154:157], v230 offset:49152
	v_mfma_f32_32x32x16_bf16 v[0:15], v[108:111], v[158:161], v[0:15]
	ds_read_b128 v[158:161], v230 offset:57344
	v_mfma_f32_32x32x16_bf16 v[16:31], v[96:99], v[176:179], v[16:31]
	ds_read_b128 v[176:179], v232 offset:49152
	v_mfma_f32_32x32x16_bf16 v[16:31], v[100:103], v[180:183], v[16:31]
	ds_read_b128 v[180:183], v232 offset:57344
	v_mfma_f32_32x32x16_bf16 v[16:31], v[104:107], v[216:219], v[16:31]
	ds_read_b128 v[216:219], v238 offset:49152
	v_mfma_f32_32x32x16_bf16 v[16:31], v[108:111], v[220:223], v[16:31]
	ds_read_b128 v[220:223], v238 offset:57344
	v_mfma_f32_32x32x16_bf16 v[32:47], v[96:99], v[224:227], v[32:47]
	ds_read_b128 v[224:227], v203 offset:49152
	v_mfma_f32_32x32x16_bf16 v[32:47], v[100:103], v[234:237], v[32:47]
	ds_read_b128 v[234:237], v203 offset:57344
	v_mfma_f32_32x32x16_bf16 v[32:47], v[104:107], v[240:243], v[32:47]
	ds_read_b128 v[240:243], v205 offset:49152
	v_mfma_f32_32x32x16_bf16 v[32:47], v[108:111], v[244:247], v[32:47]
	ds_read_b128 v[244:247], v205 offset:57344
	v_mfma_f32_32x32x16_bf16 v[48:63], v[96:99], v[248:251], v[48:63]
	ds_read_b128 v[248:251], v214 offset:49152
	v_mfma_f32_32x32x16_bf16 v[48:63], v[100:103], v[196:199], v[48:63]
	ds_read_b128 v[196:199], v214 offset:57344
	v_mfma_f32_32x32x16_bf16 v[48:63], v[104:107], v[206:209], v[48:63]
	ds_read_b128 v[206:209], v175 offset:49152
	v_mfma_f32_32x32x16_bf16 v[48:63], v[108:111], v[210:213], v[48:63]
	ds_read_b128 v[210:213], v175 offset:57344
	s_setprio 0
	s_waitcnt vmcnt(0)
	s_barrier
; #define SBAR() __builtin_amdgcn_sched_barrier(0)
; #define NAM(P0, P1, t) do { if constexpr (NA) na_mask(P0, P1, kr_lo + (t), r0, qrow, qc, c0, hi, bl); } while (0)
; #define PSM(P0, P1, MN, AL) do { if constexpr (NA) partialSM(P0, P1, m_reg, MN, AL); else { AL = 1.f; _Pragma("unroll") for (int r = 0; r < 16; ++r) P0[r] = __builtin_amdgcn_exp2f(P0[r]); } } while (0)
; #define RESCN(a) do { if constexpr (NA) RESC(a); } while (0)
; #define VM0() asm volatile("s_waitcnt vmcnt(0)" ::: "memory")
; #define NAM(P0, P1, t) do { if constexpr (NA) na_mask(P0, P1, kr_lo + (t), r0, qrow, qc, c0, hi, bl); } while (0)
; #define PSM(P0, P1, MN, AL) do { if constexpr (NA) partialSM(P0, P1, m_reg, MN, AL); else { AL = 1.f; _Pragma("unroll") for (int r = 0; r < 16; ++r) P0[r] = __builtin_amdgcn_exp2f(P0[r]); } } while (0)
; #define RESCN(a) do { if constexpr (NA) RESC(a); } while (0)
; template <bool NA, int ROWB>
; __device__ __forceinline__ void attn_dma(const bf16* __restrict__ Qb, const bf16* __restrict__ Kh, const bf16* __restrict__ Vh, bf16* __restrict__ Ob, int NT, char* lds, const int tid, float* __restrict__ ssb, int qrow0, int kr_lo, const float* bl) {
;     ...
;   for (int t = 1; t + 1 < NT; t += 2) {
;     DMA_TILE(t + 1, bn);
;     SBAR(); qkt<false>(pB0, pB1, (const bf16*)(K_lds + bc * SHM_K), qr, nullptr, r32, hi); NAM(pB0, pB1, t);
;     finishSM(pA0, pA1, alA, l_reg, pa0, pa1, pa2, pa3); SBAR();
;     pv_d0(o, vb0 + bp * (int)SHM_V, pa0, pa1, pa2, pa3); PSM(pB0, pB1, mnB, alB); RESCN(alB);
;     VM0(); __syncthreads();
;     bp = bc; bc = bn; bn = NEXTB(bn);
;     if (t + 2 < NT) DMA_TILE(t + 2, bn);
;     SBAR(); qkt<false>(pA0, pA1, (const bf16*)(K_lds + bc * SHM_K), qr, nullptr, r32, hi); NAM(pA0, pA1, t + 1);
;     finishSM(pB0, pB1, alB, l_reg, pa0, pa1, pa2, pa3); SBAR();
;     pv_d0(o, vb0 + bp * (int)SHM_V, pa0, pa1, pa2, pa3); PSM(pA0, pA1, mnA, alA); RESCN(alA);
	v_add_f32_e32 v112, v80, v112
	v_add_f32_e32 v112, v81, v112
	v_add_f32_e32 v112, v82, v112
	v_add_f32_e32 v112, v83, v112
	v_add_f32_e32 v112, v84, v112
	v_add_f32_e32 v112, v85, v112
	v_add_f32_e32 v112, v86, v112
	v_add_f32_e32 v112, v87, v112
	v_add_f32_e32 v112, v88, v112
	v_add_f32_e32 v112, v89, v112
	v_add_f32_e32 v112, v90, v112
	v_add_f32_e32 v112, v91, v112
	v_add_f32_e32 v112, v92, v112
	v_add_f32_e32 v112, v93, v112
	v_add_f32_e32 v112, v94, v112
	v_add_f32_e32 v112, v95, v112
	v_add_f32_e32 v112, v64, v112
	v_add_f32_e32 v112, v65, v112
	v_add_f32_e32 v112, v66, v112
	v_add_f32_e32 v112, v67, v112
	v_add_f32_e32 v112, v68, v112
	v_add_f32_e32 v112, v69, v112
	v_add_f32_e32 v112, v70, v112
	v_add_f32_e32 v112, v71, v112
	v_add_f32_e32 v112, v72, v112
	v_add_f32_e32 v112, v73, v112
	v_add_f32_e32 v112, v74, v112
	v_add_f32_e32 v112, v75, v112
	v_add_f32_e32 v112, v76, v112
	v_add_f32_e32 v112, v77, v112
	v_add_f32_e32 v112, v78, v112
	v_add_f32_e32 v112, v79, v112
	s_add_u32 s100, s42, s18
	s_addc_u32 s101, s43, 0
	s_add_i32 s18, s18, 0x4000
	s_and_b32 s18, s18, 0x1fffff
	s_add_u32 s98, s40, s18
	s_addc_u32 s99, s41, 0
	s_add_i32 s1, s24, s4
	s_add_i32 s25, s17, s4
	s_add_i32 m0, s1, 0xc000
	s_nop 0
	global_load_lds_dwordx4 v164, s[98:99]
	s_mov_b32 m0, s25
	s_nop 0
	global_load_lds_dwordx4 v166, s[100:101]
	s_add_i32 m0, s1, 0xc400
	s_nop 0
	global_load_lds_dwordx4 v168, s[98:99]
	s_add_i32 m0, s25, 0x400
	s_nop 0
	global_load_lds_dwordx4 v170, s[100:101]
	s_mov_b32 s1, s24
	s_mov_b32 s24, s0
	s_mov_b32 s0, s17
	s_mov_b32 s17, s1
	v_add_u32_e32 v215, s24, v195
	v_add_u32_e32 v229, s0, v187
	v_add_u32_e32 v230, s0, v188
	v_add_u32_e32 v232, s0, v189
	v_add_u32_e32 v238, s0, v190
	v_add_u32_e32 v203, s0, v191
	v_add_u32_e32 v205, s0, v192
	v_add_u32_e32 v214, s0, v193
	v_add_u32_e32 v175, s0, v194
	s_waitcnt lgkmcnt(0)
	s_barrier
.Lgqa_loop:
	s_setprio 1
	v_mfma_f32_32x32x16_bf16 v[80:95], v[146:149], v[138:141], 0
	ds_read_b64_tr_b16 v[146:147], v215 offset:0
	ds_read_b64_tr_b16 v[148:149], v215 offset:2048
	v_mfma_f32_32x32x16_bf16 v[64:79], v[150:153], v[138:141], 0
	ds_read_b64_tr_b16 v[150:151], v215 offset:4096
	ds_read_b64_tr_b16 v[152:153], v215 offset:6144
	v_mfma_f32_32x32x16_bf16 v[80:95], v[154:157], v[142:145], v[80:95]
	ds_read_b64_tr_b16 v[154:155], v215 offset:8192
	ds_read_b64_tr_b16 v[156:157], v215 offset:10240
	v_mfma_f32_32x32x16_bf16 v[64:79], v[158:161], v[142:145], v[64:79]
	ds_read_b64_tr_b16 v[158:159], v215 offset:12288
	ds_read_b64_tr_b16 v[160:161], v215 offset:14336
	v_mfma_f32_32x32x16_bf16 v[80:95], v[176:179], v[134:137], v[80:95]
	ds_read_b64_tr_b16 v[176:177], v215 offset:512
	ds_read_b64_tr_b16 v[178:179], v215 offset:2560
	v_mfma_f32_32x32x16_bf16 v[64:79], v[180:183], v[134:137], v[64:79]
	ds_read_b64_tr_b16 v[180:181], v215 offset:4608
	ds_read_b64_tr_b16 v[182:183], v215 offset:6656
	v_mfma_f32_32x32x16_bf16 v[80:95], v[216:219], v[114:117], v[80:95]
	ds_read_b64_tr_b16 v[216:217], v215 offset:8704
	ds_read_b64_tr_b16 v[218:219], v215 offset:10752
	v_mfma_f32_32x32x16_bf16 v[64:79], v[220:223], v[114:117], v[64:79]
	ds_read_b64_tr_b16 v[220:221], v215 offset:12800
	ds_read_b64_tr_b16 v[222:223], v215 offset:14848
	v_mfma_f32_32x32x16_bf16 v[80:95], v[224:227], v[118:121], v[80:95]
	ds_read_b64_tr_b16 v[224:225], v215 offset:1024
	ds_read_b64_tr_b16 v[226:227], v215 offset:3072
	v_mfma_f32_32x32x16_bf16 v[64:79], v[234:237], v[118:121], v[64:79]
	ds_read_b64_tr_b16 v[234:235], v215 offset:5120
	ds_read_b64_tr_b16 v[236:237], v215 offset:7168
	v_mfma_f32_32x32x16_bf16 v[80:95], v[240:243], v[122:125], v[80:95]
	ds_read_b64_tr_b16 v[240:241], v215 offset:9216
	ds_read_b64_tr_b16 v[242:243], v215 offset:11264
	v_mfma_f32_32x32x16_bf16 v[64:79], v[244:247], v[122:125], v[64:79]
	ds_read_b64_tr_b16 v[244:245], v215 offset:13312
	ds_read_b64_tr_b16 v[246:247], v215 offset:15360
	v_mfma_f32_32x32x16_bf16 v[80:95], v[248:251], v[126:129], v[80:95]
	ds_read_b64_tr_b16 v[248:249], v215 offset:1536
	ds_read_b64_tr_b16 v[250:251], v215 offset:3584
	v_mfma_f32_32x32x16_bf16 v[64:79], v[196:199], v[126:129], v[64:79]
	ds_read_b64_tr_b16 v[196:197], v215 offset:5632
	ds_read_b64_tr_b16 v[198:199], v215 offset:7680
	v_mfma_f32_32x32x16_bf16 v[80:95], v[206:209], v[130:133], v[80:95]
	ds_read_b64_tr_b16 v[206:207], v215 offset:9728
	ds_read_b64_tr_b16 v[208:209], v215 offset:11776
	v_mfma_f32_32x32x16_bf16 v[64:79], v[210:213], v[130:133], v[64:79]
	ds_read_b64_tr_b16 v[210:211], v215 offset:13824
	ds_read_b64_tr_b16 v[212:213], v215 offset:15872
	s_setprio 0
	s_barrier
	s_nop 7
	v_exp_f32_e32 v80, v80
	v_exp_f32_e32 v81, v81
	v_exp_f32_e32 v82, v82
	v_exp_f32_e32 v83, v83
	v_exp_f32_e32 v84, v84
	v_exp_f32_e32 v85, v85
	v_exp_f32_e32 v86, v86
	v_exp_f32_e32 v87, v87
	v_exp_f32_e32 v88, v88
	v_exp_f32_e32 v89, v89
	v_exp_f32_e32 v90, v90
	v_exp_f32_e32 v91, v91
	v_exp_f32_e32 v92, v92
	v_exp_f32_e32 v93, v93
	v_exp_f32_e32 v94, v94
	v_exp_f32_e32 v95, v95
	v_exp_f32_e32 v64, v64
	v_exp_f32_e32 v65, v65
	v_exp_f32_e32 v66, v66
	v_exp_f32_e32 v67, v67
	v_exp_f32_e32 v68, v68
	v_exp_f32_e32 v69, v69
	v_exp_f32_e32 v70, v70
	v_exp_f32_e32 v71, v71
	v_exp_f32_e32 v72, v72
	v_exp_f32_e32 v73, v73
	v_exp_f32_e32 v74, v74
	v_exp_f32_e32 v75, v75
	v_exp_f32_e32 v76, v76
	v_exp_f32_e32 v77, v77
	v_exp_f32_e32 v78, v78
	v_exp_f32_e32 v79, v79
	v_cvt_pk_bf16_f32 v96, v80, v81
	v_cvt_pk_bf16_f32 v97, v82, v83
	v_cvt_pk_bf16_f32 v98, v84, v85
	v_cvt_pk_bf16_f32 v99, v86, v87
	v_cvt_pk_bf16_f32 v100, v88, v89
	v_cvt_pk_bf16_f32 v101, v90, v91
	v_cvt_pk_bf16_f32 v102, v92, v93
	v_cvt_pk_bf16_f32 v103, v94, v95
	v_cvt_pk_bf16_f32 v104, v64, v65
	v_cvt_pk_bf16_f32 v105, v66, v67
	v_cvt_pk_bf16_f32 v106, v68, v69
	v_cvt_pk_bf16_f32 v107, v70, v71
	v_cvt_pk_bf16_f32 v108, v72, v73
	v_cvt_pk_bf16_f32 v109, v74, v75
	v_cvt_pk_bf16_f32 v110, v76, v77
	v_cvt_pk_bf16_f32 v111, v78, v79
	s_waitcnt lgkmcnt(0)
	s_barrier
; #define SBAR() __builtin_amdgcn_sched_barrier(0)
; #define NAM(P0, P1, t) do { if constexpr (NA) na_mask(P0, P1, kr_lo + (t), r0, qrow, qc, c0, hi, bl); } while (0)
; #define PSM(P0, P1, MN, AL) do { if constexpr (NA) partialSM(P0, P1, m_reg, MN, AL); else { AL = 1.f; _Pragma("unroll") for (int r = 0; r < 16; ++r) P0[r] = __builtin_amdgcn_exp2f(P0[r]); } } while (0)
; #define RESCN(a) do { if constexpr (NA) RESC(a); } while (0)
; #define VM0() asm volatile("s_waitcnt vmcnt(0)" ::: "memory")
; #define NAM(P0, P1, t) do { if constexpr (NA) na_mask(P0, P1, kr_lo + (t), r0, qrow, qc, c0, hi, bl); } while (0)
; #define PSM(P0, P1, MN, AL) do { if constexpr (NA) partialSM(P0, P1, m_reg, MN, AL); else { AL = 1.f; _Pragma("unroll") for (int r = 0; r < 16; ++r) P0[r] = __builtin_amdgcn_exp2f(P0[r]); } } while (0)
; #define RESCN(a) do { if constexpr (NA) RESC(a); } while (0)
; template <bool NA, int ROWB>
; __device__ __forceinline__ void attn_dma(const bf16* __restrict__ Qb, const bf16* __restrict__ Kh, const bf16* __restrict__ Vh, bf16* __restrict__ Ob, int NT, char* lds, const int tid, float* __restrict__ ssb, int qrow0, int kr_lo, const float* bl) {
;     ...
;   for (int t = 1; t + 1 < NT; t += 2) {
;     DMA_TILE(t + 1, bn);
;     SBAR(); qkt<false>(pB0, pB1, (const bf16*)(K_lds + bc * SHM_K), qr, nullptr, r32, hi); NAM(pB0, pB1, t);
;     finishSM(pA0, pA1, alA, l_reg, pa0, pa1, pa2, pa3); SBAR();
;     pv_d0(o, vb0 + bp * (int)SHM_V, pa0, pa1, pa2, pa3); PSM(pB0, pB1, mnB, alB); RESCN(alB);
;     VM0(); __syncthreads();
;     bp = bc; bc = bn; bn = NEXTB(bn);
;     if (t + 2 < NT) DMA_TILE(t + 2, bn);
;     SBAR(); qkt<false>(pA0, pA1, (const bf16*)(K_lds + bc * SHM_K), qr, nullptr, r32, hi); NAM(pA0, pA1, t + 1);
;     finishSM(pB0, pB1, alB, l_reg, pa0, pa1, pa2, pa3); SBAR();
;     pv_d0(o, vb0 + bp * (int)SHM_V, pa0, pa1, pa2, pa3); PSM(pA0, pA1, mnA, alA); RESCN(alA);
;     VM0(); __syncthreads();
;     bp = bc; bc = bn; bn = NEXTB(bn);
;   }
;   SBAR(); qkt<false>(pB0, pB1, (const bf16*)(K_lds + bc * SHM_K), qr, nullptr, r32, hi); NAM(pB0, pB1, NT - 1);
	s_setprio 1
	v_mfma_f32_32x32x16_bf16 v[0:15], v[96:99], v[146:149], v[0:15]
	ds_read_b128 v[146:149], v229 offset:49152
	v_mfma_f32_32x32x16_bf16 v[0:15], v[100:103], v[150:153], v[0:15]
	ds_read_b128 v[150:153], v229 offset:57344
	v_mfma_f32_32x32x16_bf16 v[0:15], v[104:107], v[154:157], v[0:15]
	ds_read_b128 v[154:157], v230 offset:49152
	v_mfma_f32_32x32x16_bf16 v[0:15], v[108:111], v[158:161], v[0:15]
	ds_read_b128 v[158:161], v230 offset:57344
	v_mfma_f32_32x32x16_bf16 v[16:31], v[96:99], v[176:179], v[16:31]
	ds_read_b128 v[176:179], v232 offset:49152
	v_mfma_f32_32x32x16_bf16 v[16:31], v[100:103], v[180:183], v[16:31]
	ds_read_b128 v[180:183], v232 offset:57344
	v_mfma_f32_32x32x16_bf16 v[16:31], v[104:107], v[216:219], v[16:31]
	ds_read_b128 v[216:219], v238 offset:49152
	v_mfma_f32_32x32x16_bf16 v[16:31], v[108:111], v[220:223], v[16:31]
	ds_read_b128 v[220:223], v238 offset:57344
	v_mfma_f32_32x32x16_bf16 v[32:47], v[96:99], v[224:227], v[32:47]
	ds_read_b128 v[224:227], v203 offset:49152
	v_mfma_f32_32x32x16_bf16 v[32:47], v[100:103], v[234:237], v[32:47]
	ds_read_b128 v[234:237], v203 offset:57344
	v_mfma_f32_32x32x16_bf16 v[32:47], v[104:107], v[240:243], v[32:47]
	ds_read_b128 v[240:243], v205 offset:49152
	v_mfma_f32_32x32x16_bf16 v[32:47], v[108:111], v[244:247], v[32:47]
	ds_read_b128 v[244:247], v205 offset:57344
	v_mfma_f32_32x32x16_bf16 v[48:63], v[96:99], v[248:251], v[48:63]
	ds_read_b128 v[248:251], v214 offset:49152
	v_mfma_f32_32x32x16_bf16 v[48:63], v[100:103], v[196:199], v[48:63]
	ds_read_b128 v[196:199], v214 offset:57344
	v_mfma_f32_32x32x16_bf16 v[48:63], v[104:107], v[206:209], v[48:63]
	ds_read_b128 v[206:209], v175 offset:49152
	v_mfma_f32_32x32x16_bf16 v[48:63], v[108:111], v[210:213], v[48:63]
	ds_read_b128 v[210:213], v175 offset:57344
	s_setprio 0
	s_waitcnt vmcnt(0)
	s_barrier
	v_add_f32_e32 v112, v80, v112
	v_add_f32_e32 v112, v81, v112
	v_add_f32_e32 v112, v82, v112
	v_add_f32_e32 v112, v83, v112
	v_add_f32_e32 v112, v84, v112
	v_add_f32_e32 v112, v85, v112
	v_add_f32_e32 v112, v86, v112
	v_add_f32_e32 v112, v87, v112
	v_add_f32_e32 v112, v88, v112
	v_add_f32_e32 v112, v89, v112
	v_add_f32_e32 v112, v90, v112
	v_add_f32_e32 v112, v91, v112
	v_add_f32_e32 v112, v92, v112
	v_add_f32_e32 v112, v93, v112
	v_add_f32_e32 v112, v94, v112
	v_add_f32_e32 v112, v95, v112
	v_add_f32_e32 v112, v64, v112
	v_add_f32_e32 v112, v65, v112
	v_add_f32_e32 v112, v66, v112
	v_add_f32_e32 v112, v67, v112
	v_add_f32_e32 v112, v68, v112
	v_add_f32_e32 v112, v69, v112
	v_add_f32_e32 v112, v70, v112
	v_add_f32_e32 v112, v71, v112
	v_add_f32_e32 v112, v72, v112
	v_add_f32_e32 v112, v73, v112
	v_add_f32_e32 v112, v74, v112
	v_add_f32_e32 v112, v75, v112
	v_add_f32_e32 v112, v76, v112
	v_add_f32_e32 v112, v77, v112
	v_add_f32_e32 v112, v78, v112
	v_add_f32_e32 v112, v79, v112
	s_add_u32 s100, s42, s18
	s_addc_u32 s101, s43, 0
	s_add_i32 s18, s18, 0x4000
	s_and_b32 s18, s18, 0x1fffff
	s_add_u32 s98, s40, s18
	s_addc_u32 s99, s41, 0
	s_add_i32 s1, s24, s4
	s_add_i32 s25, s17, s4
	s_add_i32 m0, s1, 0xc000
	s_nop 0
	global_load_lds_dwordx4 v164, s[98:99]
	s_mov_b32 m0, s25
	s_nop 0
	global_load_lds_dwordx4 v166, s[100:101]
	s_add_i32 m0, s1, 0xc400
	s_nop 0
	global_load_lds_dwordx4 v168, s[98:99]
	s_add_i32 m0, s25, 0x400
	s_nop 0
	global_load_lds_dwordx4 v170, s[100:101]
	s_mov_b32 s1, s24
	s_mov_b32 s24, s0
	s_mov_b32 s0, s17
	s_mov_b32 s17, s1
	v_add_u32_e32 v215, s24, v195
	v_add_u32_e32 v229, s0, v187
	v_add_u32_e32 v230, s0, v188
	v_add_u32_e32 v232, s0, v189
	v_add_u32_e32 v238, s0, v190
	v_add_u32_e32 v203, s0, v191
	v_add_u32_e32 v205, s0, v192
	v_add_u32_e32 v214, s0, v193
	v_add_u32_e32 v175, s0, v194
	s_waitcnt lgkmcnt(0)
	s_barrier
	s_add_i32 s16, s16, 1
	s_cmp_eq_u32 s16, 125
	s_cbranch_scc0 .Lgqa_loop
	s_setprio 1
	v_mfma_f32_32x32x16_bf16 v[80:95], v[146:149], v[138:141], 0
	v_mfma_f32_32x32x16_bf16 v[64:79], v[150:153], v[138:141], 0
	v_mfma_f32_32x32x16_bf16 v[80:95], v[154:157], v[142:145], v[80:95]
	v_mfma_f32_32x32x16_bf16 v[64:79], v[158:161], v[142:145], v[64:79]
	v_mfma_f32_32x32x16_bf16 v[80:95], v[176:179], v[134:137], v[80:95]
	v_mfma_f32_32x32x16_bf16 v[64:79], v[180:183], v[134:137], v[64:79]
	v_mfma_f32_32x32x16_bf16 v[80:95], v[216:219], v[114:117], v[80:95]
	v_mfma_f32_32x32x16_bf16 v[64:79], v[220:223], v[114:117], v[64:79]
	v_mfma_f32_32x32x16_bf16 v[80:95], v[224:227], v[118:121], v[80:95]
	v_mfma_f32_32x32x16_bf16 v[64:79], v[234:237], v[118:121], v[64:79]
	v_mfma_f32_32x32x16_bf16 v[80:95], v[240:243], v[122:125], v[80:95]
	v_mfma_f32_32x32x16_bf16 v[64:79], v[244:247], v[122:125], v[64:79]
	v_mfma_f32_32x32x16_bf16 v[80:95], v[248:251], v[126:129], v[80:95]
	v_mfma_f32_32x32x16_bf16 v[64:79], v[196:199], v[126:129], v[64:79]
	v_mfma_f32_32x32x16_bf16 v[80:95], v[206:209], v[130:133], v[80:95]
	v_mfma_f32_32x32x16_bf16 v[64:79], v[210:213], v[130:133], v[64:79]
	s_setprio 0
	s_waitcnt vmcnt(0)
	s_barrier
	s_cmp_ge_u32 s4, 0x2000
	s_cbranch_scc1 .Lgqa_trail
	s_barrier
